# cross-attention prompt units: 16 eight-byte output stores per wave paired into 8 sixteen-byte stores (permlane swaps)
# speedup vs baseline: 1.0107x; 1.0051x over previous
; template <bool SAMPLE>
; __device__ __forceinline__ void xattn_unit(const bf16_t* XQ, const bf16_t* MKVl, const float* cmem, bf16_t* XO, LAS unsigned char* lds, int u, int next, u32x4 (&kpre)[8], int wave) {
;     ...
; #pragma unroll 1
;         for (int kk = 0; kk < 4; ++kk) {
;             const int kq = hf * 4 + kk;
;             u32x4 pw = P[0];
; #pragma unroll
;             for (int q = 1; q < 8; ++q) if (kq == q) pw = P[q];
;             const bf16x8 pb = __builtin_bit_cast(bf16x8, pw);
; #pragma unroll
;             for (int n = 0; n < NO; ++n) {
;                 const s16x4 lo = vtr(trp + kk * 32 * 544 + n * 32), hi = vtr(trp + kk * 32 * 544 + 16 * 544 + n * 32);
;                 bf16x8 va; va[0] = lo[0]; va[1] = lo[1]; va[2] = lo[2]; va[3] = lo[3]; va[4] = hi[0]; va[5] = hi[1]; va[6] = hi[2]; va[7] = hi[3];
;                 O[n] = __builtin_amdgcn_mfma_f32_16x16x32_bf16(va, pb, O[n], 0, 0, 0);
;             }
;         }
.LBB0_2103:
	s_add_i32 s22, s1, s4
	s_cmpk_eq_i32 s22, 0x4400
	s_cselect_b64 vcc, -1, 0
	s_cmpk_eq_u32 s22, 0x8800
	v_cndmask_b32_e32 v130, v3, v83, vcc
	v_cndmask_b32_e32 v131, v76, v84, vcc
	v_cndmask_b32_e32 v132, v1, v77, vcc
	v_cndmask_b32_e32 v133, v0, v82, vcc
	s_cselect_b64 vcc, -1, 0
	s_cmpk_eq_u32 s22, 0xcc00
	v_cndmask_b32_e32 v133, v133, v90, vcc
	v_cndmask_b32_e32 v132, v132, v85, vcc
	v_cndmask_b32_e32 v131, v131, v92, vcc
	v_cndmask_b32_e32 v130, v130, v91, vcc
	s_cselect_b64 vcc, -1, 0
	s_cmp_eq_u32 s22, 0x11000
	v_cndmask_b32_e32 v130, v130, v95, vcc
	v_cndmask_b32_e32 v131, v131, v100, vcc
	v_cndmask_b32_e32 v132, v132, v93, vcc
	v_cndmask_b32_e32 v133, v133, v94, vcc
	s_cselect_b64 vcc, -1, 0
	s_cmp_eq_u32 s22, 0x15400
	v_cndmask_b32_e32 v133, v133, v102, vcc
	v_cndmask_b32_e32 v132, v132, v101, vcc
	v_cndmask_b32_e32 v131, v131, v104, vcc
	v_cndmask_b32_e32 v130, v130, v103, vcc
	s_cselect_b64 vcc, -1, 0
	s_cmp_eq_u32 s22, 0x19800
	v_cndmask_b32_e32 v130, v130, v111, vcc
	v_cndmask_b32_e32 v131, v131, v112, vcc
	v_cndmask_b32_e32 v132, v132, v105, vcc
	v_cndmask_b32_e32 v133, v133, v110, vcc
	s_cselect_b64 vcc, -1, 0
	s_cmp_eq_u32 s22, 0x1dc00
	v_cndmask_b32_e32 v138, v133, v118, vcc
	v_cndmask_b32_e32 v139, v132, v113, vcc
	v_cndmask_b32_e32 v131, v131, v120, vcc
	v_cndmask_b32_e32 v130, v130, v119, vcc
	s_cselect_b64 vcc, -1, 0
	v_add_u32_e32 v146, s4, v137
	v_cndmask_b32_e32 v133, v130, v127, vcc
	v_cndmask_b32_e32 v132, v131, v128, vcc
	v_cndmask_b32_e32 v131, v139, v121, vcc
	v_cndmask_b32_e32 v130, v138, v126, vcc
	ds_read_b64_tr_b16 v[140:141], v146 offset:8704
	ds_read_b64_tr_b16 v[138:139], v146
	ds_read_b64_tr_b16 v[142:143], v146 offset:32
	s_waitcnt lgkmcnt(1)
	v_mfma_f32_16x16x32_bf16 v[122:125], v[138:141], v[130:133], v[122:125]
	ds_read_b64_tr_b16 v[144:145], v146 offset:8736
	ds_read_b64_tr_b16 v[138:139], v146 offset:64
	ds_read_b64_tr_b16 v[140:141], v146 offset:8768
	s_addk_i32 s4, 0x4400
	s_waitcnt lgkmcnt(0)
	v_mfma_f32_16x16x32_bf16 v[106:109], v[138:141], v[130:133], v[106:109]
	ds_read_b64_tr_b16 v[138:139], v146 offset:96
	ds_read_b64_tr_b16 v[140:141], v146 offset:8800
	s_cmp_eq_u32 s4, 0x11000
	s_waitcnt lgkmcnt(0)
	v_mfma_f32_16x16x32_bf16 v[96:99], v[138:141], v[130:133], v[96:99]
	ds_read_b64_tr_b16 v[138:139], v146 offset:128
	ds_read_b64_tr_b16 v[140:141], v146 offset:8832
	s_waitcnt lgkmcnt(0)
	v_mfma_f32_16x16x32_bf16 v[86:89], v[138:141], v[130:133], v[86:89]
	ds_read_b64_tr_b16 v[138:139], v146 offset:160
	ds_read_b64_tr_b16 v[140:141], v146 offset:8864
	s_waitcnt lgkmcnt(0)
	v_mfma_f32_16x16x32_bf16 v[78:81], v[138:141], v[130:133], v[78:81]
	ds_read_b64_tr_b16 v[138:139], v146 offset:192
	ds_read_b64_tr_b16 v[140:141], v146 offset:8896
	s_waitcnt lgkmcnt(0)
	v_mfma_f32_16x16x32_bf16 v[72:75], v[138:141], v[130:133], v[72:75]
	ds_read_b64_tr_b16 v[138:139], v146 offset:224
	ds_read_b64_tr_b16 v[140:141], v146 offset:8928
	s_waitcnt lgkmcnt(0)
	v_mfma_f32_16x16x32_bf16 v[68:71], v[138:141], v[130:133], v[68:71]
	ds_read_b64_tr_b16 v[138:139], v146 offset:256
	ds_read_b64_tr_b16 v[140:141], v146 offset:8960
	s_waitcnt lgkmcnt(0)
	v_mfma_f32_16x16x32_bf16 v[64:67], v[138:141], v[130:133], v[64:67]
	ds_read_b64_tr_b16 v[138:139], v146 offset:288
	ds_read_b64_tr_b16 v[140:141], v146 offset:8992
	s_waitcnt lgkmcnt(0)
	v_mfma_f32_16x16x32_bf16 v[60:63], v[138:141], v[130:133], v[60:63]
	ds_read_b64_tr_b16 v[138:139], v146 offset:320
	ds_read_b64_tr_b16 v[140:141], v146 offset:9024
	s_waitcnt lgkmcnt(0)
	v_mfma_f32_16x16x32_bf16 v[56:59], v[138:141], v[130:133], v[56:59]
	ds_read_b64_tr_b16 v[138:139], v146 offset:352
	ds_read_b64_tr_b16 v[140:141], v146 offset:9056
	s_waitcnt lgkmcnt(0)
	v_mfma_f32_16x16x32_bf16 v[52:55], v[138:141], v[130:133], v[52:55]
	ds_read_b64_tr_b16 v[138:139], v146 offset:384
	ds_read_b64_tr_b16 v[140:141], v146 offset:9088
	s_waitcnt lgkmcnt(0)
	v_mfma_f32_16x16x32_bf16 v[48:51], v[138:141], v[130:133], v[48:51]
	ds_read_b64_tr_b16 v[138:139], v146 offset:416
	ds_read_b64_tr_b16 v[140:141], v146 offset:9120
	s_waitcnt lgkmcnt(0)
	v_mfma_f32_16x16x32_bf16 v[44:47], v[138:141], v[130:133], v[44:47]
	ds_read_b64_tr_b16 v[138:139], v146 offset:448
	ds_read_b64_tr_b16 v[140:141], v146 offset:9152
	s_waitcnt lgkmcnt(0)
	v_mfma_f32_16x16x32_bf16 v[40:43], v[138:141], v[130:133], v[40:43]
	ds_read_b64_tr_b16 v[138:139], v146 offset:480
	ds_read_b64_tr_b16 v[140:141], v146 offset:9184
	v_mfma_f32_16x16x32_bf16 v[114:117], v[142:145], v[130:133], v[114:117]
	s_waitcnt lgkmcnt(0)
	v_mfma_f32_16x16x32_bf16 v[4:7], v[138:141], v[130:133], v[4:7]
	s_cbranch_scc0 .LBB0_2103
	s_mov_b32 s1, 4
	s_mov_b64 s[40:41], 0
	s_mov_b64 s[42:43], -1
	s_and_b64 vcc, exec, s[6:7]
	s_cbranch_vccz .LBB0_2100
; __device__ __forceinline__ unsigned pk2(float lo, float hi) { const f32x2_t v = {lo, hi}; const bf16x2_t b = __builtin_convertvector(v, bf16x2_t); return __builtin_bit_cast(unsigned, b); }
; __device__ __forceinline__ u32x2 pk4(f32x4 v) { u32x2 r; r.x = pk2(v.x, v.y); r.y = pk2(v.z, v.w); return r; }
; #define WG_BAR() do { asm volatile("s_waitcnt lgkmcnt(0)" ::: "memory"); __builtin_amdgcn_s_barrier(); asm volatile("" ::: "memory"); } while (0)
; template <bool SAMPLE>
; __device__ __forceinline__ void xattn_unit(const bf16_t* XQ, const bf16_t* MKVl, const float* cmem, bf16_t* XO, LAS unsigned char* lds, int u, int next, u32x4 (&kpre)[8], int wave) {
;     ...
;     float den = 0.f;
; #pragma unroll
;     for (int kt = 0; kt < 16; ++kt) { S[kt].x = __builtin_amdgcn_exp2f(S[kt].x - m); S[kt].y = __builtin_amdgcn_exp2f(S[kt].y - m); S[kt].z = __builtin_amdgcn_exp2f(S[kt].z - m); S[kt].w = __builtin_amdgcn_exp2f(S[kt].w - m); den += (S[kt].x + S[kt].y) + (S[kt].z + S[kt].w); }
;     den += __shfl_xor(den, 16); den += __shfl_xor(den, 32);
;     u32x4 P[8];
; #pragma unroll
;     for (int kk = 0; kk < 8; ++kk) { P[kk].x = pk2(S[2 * kk].x, S[2 * kk].y); P[kk].y = pk2(S[2 * kk].z, S[2 * kk].w); P[kk].z = pk2(S[2 * kk + 1].x, S[2 * kk + 1].y); P[kk].w = pk2(S[2 * kk + 1].z, S[2 * kk + 1].w); }
;     WG_BAR();
;     xa_store(kpre, bufA, 544, tid);
;     WG_BAR();
;     const float inv = 1.f / den;
;     ...
;     else { bf16_t* op = XO + qrow * DM + h * 256 + 4 * fq;
; #pragma unroll
;         for (int n = 0; n < NO; ++n) *(u32x2*)(op + 16 * n) = pk4(O[n] * inv); }
	v_add_f32_e32 v1, v129, v134
	ds_bpermute_b32 v3, v164, v1
	v_readlane_b32 s6, v254, 32
	v_readlane_b32 s7, v254, 33
	v_lshlrev_b32_e32 v0, 2, v182
	s_lshl_b32 s4, s0, 1
	s_waitcnt lgkmcnt(0)
	v_add_f32_e32 v1, v1, v3
	s_waitcnt vmcnt(7)
	v_lshl_add_u64 v[8:9], v[180:181], 1, s[6:7]
	v_div_scale_f32 v3, s[6:7], v1, v1, 1.0
	v_rcp_f32_e32 v10, v3
	v_div_scale_f32 v11, vcc, 1.0, v1, 1.0
	v_lshl_add_u64 v[8:9], v[8:9], 0, s[4:5]
	s_waitcnt vmcnt(6)
	v_fma_f32 v12, -v3, v10, 1.0
	v_fmac_f32_e32 v10, v12, v10
	v_mul_f32_e32 v12, v11, v10
	v_fma_f32 v13, -v3, v12, v11
	v_fmac_f32_e32 v12, v13, v10
	v_fma_f32 v3, -v3, v12, v11
	v_div_fmas_f32 v3, v3, v10, v12
	v_div_fixup_f32 v10, v3, v1, 1.0
	v_ashrrev_i32_e32 v1, 31, v0
	v_lshl_add_u64 v[0:1], v[0:1], 1, v[8:9]
	v_pk_mul_f32 v[8:9], v[10:11], v[124:125] op_sel_hi:[0,1]
	v_pk_mul_f32 v[12:13], v[10:11], v[122:123] op_sel_hi:[0,1]
	v_cvt_pk_bf16_f32 v12, v12, v13
	v_cvt_pk_bf16_f32 v13, v8, v9
	v_lshrrev_b32_e32 v146, 4, v219
	v_lshlrev_b32_e32 v146, 3, v146
	v_mov_b32_e32 v147, v2
	v_lshl_add_u64 v[146:147], v[146:147], 0, v[0:1]
	v_mov_b64_e32 v[148:149], v[12:13]
	v_pk_mul_f32 v[8:9], v[10:11], v[116:117] op_sel_hi:[0,1]
	v_pk_mul_f32 v[12:13], v[10:11], v[114:115] op_sel_hi:[0,1]
	v_cvt_pk_bf16_f32 v12, v12, v13
	v_cvt_pk_bf16_f32 v13, v8, v9
	v_mov_b64_e32 v[150:151], v[12:13]
	s_nop 1
	v_permlane32_swap_b32_e32 v148, v150
	v_permlane32_swap_b32_e32 v149, v151
	s_nop 1
	v_permlane16_swap_b32_e32 v148, v150
	v_permlane16_swap_b32_e32 v149, v151
	global_store_dwordx4 v[146:147], v[148:151], off sc0
	s_nop 0
	v_pk_mul_f32 v[8:9], v[10:11], v[108:109] op_sel_hi:[0,1]
	v_pk_mul_f32 v[12:13], v[10:11], v[106:107] op_sel_hi:[0,1]
	v_cvt_pk_bf16_f32 v12, v12, v13
	v_cvt_pk_bf16_f32 v13, v8, v9
	v_mov_b64_e32 v[148:149], v[12:13]
	v_pk_mul_f32 v[8:9], v[10:11], v[98:99] op_sel_hi:[0,1]
	v_pk_mul_f32 v[12:13], v[10:11], v[96:97] op_sel_hi:[0,1]
	v_cvt_pk_bf16_f32 v12, v12, v13
	v_cvt_pk_bf16_f32 v13, v8, v9
	v_mov_b64_e32 v[150:151], v[12:13]
	s_nop 1
	v_permlane32_swap_b32_e32 v148, v150
	v_permlane32_swap_b32_e32 v149, v151
	s_nop 1
	v_permlane16_swap_b32_e32 v148, v150
	v_permlane16_swap_b32_e32 v149, v151
	global_store_dwordx4 v[146:147], v[148:151], off offset:64 sc0
	s_nop 0
	v_pk_mul_f32 v[8:9], v[10:11], v[88:89] op_sel_hi:[0,1]
	v_pk_mul_f32 v[12:13], v[10:11], v[86:87] op_sel_hi:[0,1]
	v_cvt_pk_bf16_f32 v12, v12, v13
	v_cvt_pk_bf16_f32 v13, v8, v9
	v_mov_b64_e32 v[148:149], v[12:13]
	v_pk_mul_f32 v[8:9], v[10:11], v[80:81] op_sel_hi:[0,1]
	v_pk_mul_f32 v[12:13], v[10:11], v[78:79] op_sel_hi:[0,1]
	v_cvt_pk_bf16_f32 v12, v12, v13
	v_cvt_pk_bf16_f32 v13, v8, v9
	v_mov_b64_e32 v[150:151], v[12:13]
	s_nop 1
	v_permlane32_swap_b32_e32 v148, v150
	v_permlane32_swap_b32_e32 v149, v151
	s_nop 1
	v_permlane16_swap_b32_e32 v148, v150
	v_permlane16_swap_b32_e32 v149, v151
	global_store_dwordx4 v[146:147], v[148:151], off offset:128 sc0
	s_nop 0
	v_pk_mul_f32 v[8:9], v[10:11], v[74:75] op_sel_hi:[0,1]
	v_pk_mul_f32 v[12:13], v[10:11], v[72:73] op_sel_hi:[0,1]
	v_cvt_pk_bf16_f32 v12, v12, v13
	v_cvt_pk_bf16_f32 v13, v8, v9
	v_mov_b64_e32 v[148:149], v[12:13]
	v_pk_mul_f32 v[8:9], v[10:11], v[70:71] op_sel_hi:[0,1]
	v_pk_mul_f32 v[12:13], v[10:11], v[68:69] op_sel_hi:[0,1]
	v_cvt_pk_bf16_f32 v12, v12, v13
	v_cvt_pk_bf16_f32 v13, v8, v9
	v_mov_b64_e32 v[150:151], v[12:13]
	s_nop 1
	v_permlane32_swap_b32_e32 v148, v150
	v_permlane32_swap_b32_e32 v149, v151
	s_nop 1
	v_permlane16_swap_b32_e32 v148, v150
	v_permlane16_swap_b32_e32 v149, v151
	global_store_dwordx4 v[146:147], v[148:151], off offset:192 sc0
	s_nop 0
	v_pk_mul_f32 v[8:9], v[10:11], v[66:67] op_sel_hi:[0,1]
	v_pk_mul_f32 v[12:13], v[10:11], v[64:65] op_sel_hi:[0,1]
	v_cvt_pk_bf16_f32 v12, v12, v13
	v_cvt_pk_bf16_f32 v13, v8, v9
	v_mov_b64_e32 v[148:149], v[12:13]
	v_pk_mul_f32 v[8:9], v[10:11], v[62:63] op_sel_hi:[0,1]
	v_pk_mul_f32 v[12:13], v[10:11], v[60:61] op_sel_hi:[0,1]
	v_cvt_pk_bf16_f32 v12, v12, v13
	v_cvt_pk_bf16_f32 v13, v8, v9
	v_mov_b64_e32 v[150:151], v[12:13]
	s_nop 1
	v_permlane32_swap_b32_e32 v148, v150
	v_permlane32_swap_b32_e32 v149, v151
	s_nop 1
	v_permlane16_swap_b32_e32 v148, v150
	v_permlane16_swap_b32_e32 v149, v151
	global_store_dwordx4 v[146:147], v[148:151], off offset:256 sc0
	s_nop 0
	v_pk_mul_f32 v[8:9], v[10:11], v[58:59] op_sel_hi:[0,1]
	v_pk_mul_f32 v[12:13], v[10:11], v[56:57] op_sel_hi:[0,1]
	v_cvt_pk_bf16_f32 v12, v12, v13
	v_cvt_pk_bf16_f32 v13, v8, v9
	v_mov_b64_e32 v[148:149], v[12:13]
	v_pk_mul_f32 v[8:9], v[10:11], v[54:55] op_sel_hi:[0,1]
	v_pk_mul_f32 v[12:13], v[10:11], v[52:53] op_sel_hi:[0,1]
	v_cvt_pk_bf16_f32 v12, v12, v13
	v_cvt_pk_bf16_f32 v13, v8, v9
	v_mov_b64_e32 v[150:151], v[12:13]
	s_nop 1
	v_permlane32_swap_b32_e32 v148, v150
	v_permlane32_swap_b32_e32 v149, v151
	s_nop 1
	v_permlane16_swap_b32_e32 v148, v150
	v_permlane16_swap_b32_e32 v149, v151
	global_store_dwordx4 v[146:147], v[148:151], off offset:320 sc0
	s_nop 0
	v_pk_mul_f32 v[8:9], v[10:11], v[50:51] op_sel_hi:[0,1]
	v_pk_mul_f32 v[12:13], v[10:11], v[48:49] op_sel_hi:[0,1]
	v_cvt_pk_bf16_f32 v12, v12, v13
	v_cvt_pk_bf16_f32 v13, v8, v9
	v_mov_b64_e32 v[148:149], v[12:13]
	v_pk_mul_f32 v[8:9], v[10:11], v[46:47] op_sel_hi:[0,1]
	v_pk_mul_f32 v[12:13], v[10:11], v[44:45] op_sel_hi:[0,1]
	v_cvt_pk_bf16_f32 v12, v12, v13
	v_cvt_pk_bf16_f32 v13, v8, v9
	v_mov_b64_e32 v[150:151], v[12:13]
	s_nop 1
	v_permlane32_swap_b32_e32 v148, v150
	v_permlane32_swap_b32_e32 v149, v151
	s_nop 1
	v_permlane16_swap_b32_e32 v148, v150
	v_permlane16_swap_b32_e32 v149, v151
	global_store_dwordx4 v[146:147], v[148:151], off offset:384 sc0
	s_nop 0
	v_pk_mul_f32 v[8:9], v[10:11], v[42:43] op_sel_hi:[0,1]
	v_pk_mul_f32 v[12:13], v[10:11], v[40:41] op_sel_hi:[0,1]
	v_pk_mul_f32 v[6:7], v[10:11], v[6:7] op_sel_hi:[0,1]
	v_pk_mul_f32 v[4:5], v[10:11], v[4:5] op_sel_hi:[0,1]
	v_cvt_pk_bf16_f32 v12, v12, v13
	v_cvt_pk_bf16_f32 v13, v8, v9
	v_cvt_pk_bf16_f32 v4, v4, v5
	v_cvt_pk_bf16_f32 v5, v6, v7
	v_mov_b64_e32 v[148:149], v[12:13]
	v_mov_b64_e32 v[150:151], v[4:5]
	s_nop 1
	v_permlane32_swap_b32_e32 v148, v150
	v_permlane32_swap_b32_e32 v149, v151
	s_nop 1
	v_permlane16_swap_b32_e32 v148, v150
	v_permlane16_swap_b32_e32 v149, v151
	global_store_dwordx4 v[146:147], v[148:151], off offset:448 sc0
	s_nop 0
	s_branch .LBB0_2094
